# acquire invalidate (buffer_inv sc1) issued before the counter polls of P3/P7/P8/P9/P12 and at the arrive of the P0 grid barrier instead of behind the successful poll
# speedup vs baseline: 1.0182x; 1.0182x over previous
; __device__ __forceinline__ unsigned xb_add(unsigned* p, unsigned v) { return __hip_atomic_fetch_add(p, v, __ATOMIC_RELAXED, __HIP_MEMORY_SCOPE_AGENT); }
; __device__ __forceinline__ void xcd_barrier(const XcdBarrier& b) {
;     ...
;     if (threadIdx.x == 0) {
;         unsigned* bar = b.bar;
;         __builtin_amdgcn_s_waitcnt(0);
;         unsigned nloc = b.st[0], nx = b.st[1];
;         if (nloc == 0u) { xcd_barrier_complete(bar, b.x, nloc, nx); b.st[0] = nloc; b.st[1] = nx; }
;         const unsigned old = xb_add(&bar[XB_XSUB(b.x)], 1u);
;         const unsigned gen = old / nloc;
;         if (old + 1u == (gen + 1u) * nloc) {
.LBB0_48:
	s_mov_b64 s[8:9], exec
	s_lshl_b32 s3, s54, 8
	v_mbcnt_lo_u32_b32 v1, s8, 0
	s_add_u32 s4, s90, s3
	v_mbcnt_hi_u32_b32 v1, s9, v1
	s_addc_u32 s5, s91, 0
	v_cmp_eq_u32_e32 vcc, 0, v1
	s_and_saveexec_b64 s[10:11], vcc
	s_cbranch_execz .LBB0_50
	s_bcnt1_i32_b64 s3, s[8:9]
	v_mov_b32_e32 v4, 0x1000
	v_mov_b32_e32 v5, s3
	global_atomic_add v4, v4, v5, s[4:5] offset:1024 sc0
	buffer_inv sc1

; __device__ __forceinline__ unsigned xb_ld(unsigned* p)              { return __hip_atomic_load(p, __ATOMIC_RELAXED, __HIP_MEMORY_SCOPE_AGENT); }
; #define XB_SPIN(cond, bar) do { unsigned _sp = 0; while (cond) { __builtin_amdgcn_s_sleep(1); \
;     if ((++_sp & 255u) == 0u) { if (xb_ld(&(bar)[XB_TMO])) break; if (_sp > XB_SPIN_CAP) { atomicAdd(&(bar)[XB_TMO], 1u); break; } } } } while (0)
; __device__ __forceinline__ void xcd_barrier(const XcdBarrier& b) {
;     ...
;         XB_SPIN(xb_ld(&bar[XB_XGEN(b.x)]) == gen, bar);
;         __builtin_amdgcn_fence(__ATOMIC_ACQUIRE, "agent");
;         asm volatile("s_waitcnt vmcnt(0)" ::: "memory");
.LBB0_98:
	s_or_b64 exec, exec, s[4:5]
	s_waitcnt vmcnt(0)
	s_waitcnt vmcnt(0)

; __device__ __forceinline__ unsigned xb_ld(unsigned* p)              { return __hip_atomic_load(p, __ATOMIC_RELAXED, __HIP_MEMORY_SCOPE_AGENT); }
; #define XB_SPIN(cond, bar) do { unsigned _sp = 0; while (cond) { __builtin_amdgcn_s_sleep(1); \
;     if ((++_sp & 255u) == 0u) { if (xb_ld(&(bar)[XB_TMO])) break; if (_sp > XB_SPIN_CAP) { atomicAdd(&(bar)[XB_TMO], 1u); break; } } } } while (0)
; #define PHASE_VARS() int tid = tid0; asm volatile("" : "+v"(tid)); const int lane = tid & 63, gtid = bid * NTHR + tid, gwave = gtid >> 6; (void)lane; (void)gtid; (void)gwave
; __global__ void __launch_bounds__(NTHR, 2) k_main(Args a) {
;     ...
;     if (IN(3)) {
;         PHASE_VARS();
;         __syncthreads();
;         if (tid == 0) {
;             int plo = 0, phi = T / 256 - 1;
;             if (nb == 256) { const int r0 = min(max(64 * bid - 128, 0), max(128 * (bid >> 1) - 3, 0)), r1 = max(64 * bid + 63, 128 * (bid >> 1) + 127); plo = r0 >> 8; phi = r1 >> 8; }
;             for (int p = plo; p <= phi; ++p) { unsigned* cw = &((unsigned*)ws)[8192 + 16 * p]; XB_SPIN(xb_ld(cw) < (unsigned)(PS / 256), (unsigned*)ws); }
;             __builtin_amdgcn_fence(__ATOMIC_ACQUIRE, "agent");
.LBB0_146:
	v_writelane_b32 v235, s52, 42
	s_add_u32 s0, s88, 0x1000000
	s_addc_u32 s93, s89, 0
	v_writelane_b32 v235, s53, 43
	v_writelane_b32 v235, s0, 44
	s_add_u32 s82, s90, 0x9380000
	s_addc_u32 s83, s91, 0
	v_writelane_b32 v235, s1, 45
	v_writelane_b32 v235, s2, 46
	v_writelane_b32 v235, s3, 47
	s_add_u32 s0, s90, 0x7200000
	s_addc_u32 s1, s91, 0
	s_add_u32 s52, s90, 0x9300000
	v_writelane_b32 v235, s0, 48
	s_addc_u32 s53, s91, 0
	s_add_u32 s58, s90, 0xa400000
	v_writelane_b32 v235, s1, 49
	s_addc_u32 s59, s91, 0
	v_readlane_b32 s4, v235, 40
	v_readlane_b32 s5, v235, 41
	s_cmp_lt_i32 s4, 4
	s_cselect_b64 s[0:1], -1, 0
	s_cmp_gt_i32 s5, 3
	s_cselect_b64 s[4:5], -1, 0
	s_and_b64 s[0:1], s[0:1], s[4:5]
	s_andn2_b64 vcc, exec, s[0:1]
	v_writelane_b32 v235, s58, 50
	s_nop 1
	v_writelane_b32 v235, s59, 51
	s_cbranch_vccnz .LBB0_374
	v_mov_b32_e32 v209, v0
	v_writelane_b32 v235, s62, 52
	s_mov_b32 s3, 0
	v_cmp_eq_u32_e32 vcc, 0, v209
	v_writelane_b32 v235, s63, 53
	s_barrier
	s_and_saveexec_b64 s[0:1], vcc
	s_cbranch_execz .LBB0_167
	buffer_inv sc1
	s_cmpk_lg_i32 s33, 0x100
	s_mov_b32 s14, 63
	s_cbranch_scc1 .LBB0_150
	s_lshl_b32 s3, s2, 6
	s_max_i32 s4, s3, 0x80
	s_and_b32 s3, s3, 0xffffff80
	s_max_i32 s3, s3, 3
	s_addk_i32 s4, 0xff80
	s_add_i32 s3, s3, -3
	s_min_u32 s3, s4, s3
	s_lshr_b32 s3, s3, 8
	s_ashr_i32 s14, s2, 2

; __device__ __forceinline__ unsigned xb_ld(unsigned* p)              { return __hip_atomic_load(p, __ATOMIC_RELAXED, __HIP_MEMORY_SCOPE_AGENT); }
; #define XB_SPIN(cond, bar) do { unsigned _sp = 0; while (cond) { __builtin_amdgcn_s_sleep(1); \
;     if ((++_sp & 255u) == 0u) { if (xb_ld(&(bar)[XB_TMO])) break; if (_sp > XB_SPIN_CAP) { atomicAdd(&(bar)[XB_TMO], 1u); break; } } } } while (0)
; __global__ void __launch_bounds__(NTHR, 2) k_main(Args a) {
;     ...
;             for (int p = plo; p <= phi; ++p) { unsigned* cw = &((unsigned*)ws)[8192 + 16 * p]; XB_SPIN(xb_ld(cw) < (unsigned)(PS / 256), (unsigned*)ws); }
;             __builtin_amdgcn_fence(__ATOMIC_ACQUIRE, "agent");
;             asm volatile("s_waitcnt vmcnt(0)" ::: "memory");
;         }
.LBB0_166:
	s_waitcnt vmcnt(0)
	s_waitcnt vmcnt(0)

; __device__ __forceinline__ unsigned xb_ld(unsigned* p)              { return __hip_atomic_load(p, __ATOMIC_RELAXED, __HIP_MEMORY_SCOPE_AGENT); }
; #define XB_SPIN(cond, bar) do { unsigned _sp = 0; while (cond) { __builtin_amdgcn_s_sleep(1); \
;     if ((++_sp & 255u) == 0u) { if (xb_ld(&(bar)[XB_TMO])) break; if (_sp > XB_SPIN_CAP) { atomicAdd(&(bar)[XB_TMO], 1u); break; } } } } while (0)
; #define PHASE_VARS() int tid = tid0; asm volatile("" : "+v"(tid)); const int lane = tid & 63, gtid = bid * NTHR + tid, gwave = gtid >> 6; (void)lane; (void)gtid; (void)gwave
; __global__ void __launch_bounds__(NTHR, 2) k_main(Args a) {
;     ...
;     if (IN(7)) {
;         PHASE_VARS();
;         pg8::Gemm g{MIXB, WOT, T, D, D}; pg8::StaticOrder S; S.init(T, D, nb, bid);
;         { __syncthreads();
;           if (tid == 0) { pg8::Unit u; for (int i = 0; S.next(i, u); ++i) { unsigned* cw = &((unsigned*)ws)[10240 + 16 * u.pm]; XB_SPIN(xb_ld(cw) < 4u, (unsigned*)ws); }
;               __builtin_amdgcn_fence(__ATOMIC_ACQUIRE, "agent"); asm volatile("s_waitcnt vmcnt(0)" ::: "memory"); }
.LBB0_474:
	s_cmp_lt_i32 s84, 8
	s_cselect_b64 s[0:1], -1, 0
	s_cmp_gt_i32 s85, 7
	s_cselect_b64 s[4:5], -1, 0
	s_and_b64 s[0:1], s[0:1], s[4:5]
	v_readlane_b32 s68, v235, 42
	s_andn2_b64 vcc, exec, s[0:1]
	v_readlane_b32 s69, v235, 43
	s_cbranch_vccnz .LBB0_538
	v_mov_b32_e32 v1, v0
	s_mov_b32 s3, 0
	v_cmp_eq_u32_e64 s[0:1], 0, v1
	s_barrier
	s_and_saveexec_b64 s[4:5], s[0:1]
	s_cbranch_execz .LBB0_500
	buffer_inv sc1
	s_ashr_i32 s14, s33, 31
	s_ashr_i32 s15, s2, 31
	v_mov_b64_e32 v[2:3], 0x100
	v_mov_b64_e32 v[4:5], 0xff
	v_mov_b32_e32 v1, 0xa000
	v_mov_b32_e32 v6, 0
	s_branch .LBB0_480

; __device__ __forceinline__ unsigned xb_ld(unsigned* p)              { return __hip_atomic_load(p, __ATOMIC_RELAXED, __HIP_MEMORY_SCOPE_AGENT); }
; #define XB_SPIN(cond, bar) do { unsigned _sp = 0; while (cond) { __builtin_amdgcn_s_sleep(1); \
;     if ((++_sp & 255u) == 0u) { if (xb_ld(&(bar)[XB_TMO])) break; if (_sp > XB_SPIN_CAP) { atomicAdd(&(bar)[XB_TMO], 1u); break; } } } } while (0)
; __global__ void __launch_bounds__(NTHR, 2) k_main(Args a) {
;     ...
;         for (int i = 0; S.next(i, u); ++i) {
;             __syncthreads();
;             if (tid == 0) { unsigned* cw = &((unsigned*)ws)[12288 + 16 * u.pm]; XB_SPIN(xb_ld(cw) < (unsigned)(D / 256), (unsigned*)ws);
;                 __builtin_amdgcn_fence(__ATOMIC_ACQUIRE, "agent"); asm volatile("s_waitcnt vmcnt(0)" ::: "memory"); }
;             __syncthreads();
.LBB0_549:
	s_barrier
	s_and_saveexec_b64 s[10:11], s[0:1]
	s_cbranch_execz .LBB0_564
	buffer_inv sc1
	s_lshl_b32 s24, s43, 4
	s_ashr_i32 s25, s24, 31
	s_lshl_b64 s[24:25], s[24:25], 2
	s_add_u32 s24, s90, s24
	s_addc_u32 s25, s91, s25
	global_load_dword v2, v28, s[24:25] sc1
	s_add_u32 s24, s24, 0xc000
	s_addc_u32 s25, s25, 0
	s_waitcnt vmcnt(0)
	v_cmp_lt_u32_e32 vcc, 3, v2
	s_cbranch_vccnz .LBB0_563
	s_mov_b32 s44, 1
	s_branch .LBB0_553

; __device__ __forceinline__ unsigned xb_ld(unsigned* p)              { return __hip_atomic_load(p, __ATOMIC_RELAXED, __HIP_MEMORY_SCOPE_AGENT); }
; #define XB_SPIN(cond, bar) do { unsigned _sp = 0; while (cond) { __builtin_amdgcn_s_sleep(1); \
;     if ((++_sp & 255u) == 0u) { if (xb_ld(&(bar)[XB_TMO])) break; if (_sp > XB_SPIN_CAP) { atomicAdd(&(bar)[XB_TMO], 1u); break; } } } } while (0)
; #define PHASE_VARS() int tid = tid0; asm volatile("" : "+v"(tid)); const int lane = tid & 63, gtid = bid * NTHR + tid, gwave = gtid >> 6; (void)lane; (void)gtid; (void)gwave
; __global__ void __launch_bounds__(NTHR, 2) k_main(Args a) {
;     ...
;     if (IN(9)) {
;         PHASE_VARS();
;         pg8::Gemm g{XNB, WQT, T, D, D}; pg8::StaticOrder S; S.init(T, D, nb, bid);
;         { __syncthreads();
;           if (tid == 0) { pg8::Unit u; for (int i = 0; S.next(i, u); ++i) { unsigned* cw = &((unsigned*)ws)[6144 + 16 * u.pm]; XB_SPIN(xb_ld(cw) < 4u, (unsigned*)ws); }
;               XB_SPIN(xb_ld(&((unsigned*)ws)[14336]) < 256u, (unsigned*)ws);
;               __builtin_amdgcn_fence(__ATOMIC_ACQUIRE, "agent"); asm volatile("s_waitcnt vmcnt(0)" ::: "memory"); }
.LBB0_572:
	s_cmp_lt_i32 s84, 10
	s_cselect_b64 s[0:1], -1, 0
	s_cmp_gt_i32 s85, 9
	s_cselect_b64 s[4:5], -1, 0
	s_and_b64 s[0:1], s[0:1], s[4:5]
	s_andn2_b64 vcc, exec, s[0:1]
	s_cbranch_vccnz .LBB0_645
	v_mov_b32_e32 v1, v0
	s_mov_b32 s3, 0
	v_cmp_eq_u32_e64 s[0:1], 0, v1
	s_barrier
	s_and_saveexec_b64 s[4:5], s[0:1]
	v_readlane_b32 s54, v235, 34
	v_readlane_b32 s55, v235, 35
	s_cbranch_execz .LBB0_611
	buffer_inv sc1
	v_mov_b32_e32 v9, 0xe000
	global_load_dword v8, v9, s[90:91] sc1
	s_ashr_i32 s14, s33, 31
	s_ashr_i32 s15, s2, 31
	v_mov_b64_e32 v[2:3], 0x100
	v_mov_b64_e32 v[4:5], 0xff
	v_mov_b32_e32 v1, 0x6000
	v_mov_b32_e32 v6, 0
	s_branch .LBB0_578

; __device__ __forceinline__ unsigned xb_ld(unsigned* p)              { return __hip_atomic_load(p, __ATOMIC_RELAXED, __HIP_MEMORY_SCOPE_AGENT); }
; #define XB_SPIN(cond, bar) do { unsigned _sp = 0; while (cond) { __builtin_amdgcn_s_sleep(1); \
;     if ((++_sp & 255u) == 0u) { if (xb_ld(&(bar)[XB_TMO])) break; if (_sp > XB_SPIN_CAP) { atomicAdd(&(bar)[XB_TMO], 1u); break; } } } } while (0)
; __global__ void __launch_bounds__(NTHR, 2) k_main(Args a) {
;     ...
;         for (int j = bid; j < NCHUNK; j += nb) {
;             __syncthreads();
;             if (tid == 0) {
;                 unsigned* cw = &((unsigned*)ws)[4096 + 16 * (j >> 2)];
;                 XB_SPIN(xb_ld(cw) < (unsigned)(D / 256), (unsigned*)ws);
;                 __builtin_amdgcn_fence(__ATOMIC_ACQUIRE, "agent");
;                 asm volatile("s_waitcnt vmcnt(0)" ::: "memory");
;             }
.LBB0_648:
	s_barrier
	s_and_saveexec_b64 s[10:11], s[0:1]
	s_cbranch_execz .LBB0_663
	buffer_inv sc1
	s_lshl_b32 s12, s2, 2
	s_and_b32 s12, s12, -16
	s_ashr_i32 s13, s12, 31
	s_lshl_b64 s[12:13], s[12:13], 2
	s_add_u32 s12, s90, s12
	s_addc_u32 s13, s91, s13
	global_load_dword v18, v93, s[12:13] sc1
	s_add_u32 s12, s12, 0x4000
	s_addc_u32 s13, s13, 0
	s_waitcnt vmcnt(0)
	v_cmp_lt_u32_e32 vcc, 3, v18
	s_cbranch_vccnz .LBB0_662
	s_mov_b32 s41, 1
	s_branch .LBB0_652
